# P1 writes the gate tiles (read only in P3) with streaming stores so x_rnn/g_rnn/qkv stay cache-resident for P2; on top of P1 column-reverse and P7 row-panel reverse
# speedup vs baseline: 1.0053x; 1.0053x over previous
.LBB0_275:
	s_cmp_gt_i32 s68, 13
	s_cbranch_scc1 .Lepi_in_nt
	v_lshl_add_u32 v154, s20, 8, v146
	v_ashrrev_i32_e32 v155, 31, v154
	v_lshl_add_u64 v[156:157], v[154:155], 2, s[84:85]
	global_load_dword v1, v[156:157], off
	global_load_dword v153, v[156:157], off offset:64
	global_load_dword v162, v[156:157], off offset:128
	global_load_dword v173, v[156:157], off offset:192
	global_load_dword v177, v[156:157], off offset:512
	global_load_dword v178, v[156:157], off offset:576
	global_load_dword v179, v[156:157], off offset:640
	global_load_dword v180, v[156:157], off offset:704
	v_add_u32_e32 v144, s11, v148
	v_or_b32_e32 v160, 16, v154
	v_or_b32_e32 v161, 32, v154
	v_ashrrev_i32_e32 v145, 31, v144
	v_or_b32_e32 v165, 48, v154
	v_add_u32_e32 v166, 0x80, v154
	v_add_u32_e32 v167, 0x90, v154
	v_add_u32_e32 v168, 0xa0, v154
	v_add_u32_e32 v169, 0xb0, v154
	v_mul_lo_u32 v163, s23, v154
	v_mad_u64_u32 v[158:159], s[26:27], s22, v154, 0
	v_lshl_add_u64 v[144:145], v[144:145], 1, s[24:25]
	v_mul_lo_u32 v175, s22, v155
	v_mul_lo_u32 v164, s23, v160
	v_mad_u64_u32 v[154:155], s[24:25], s22, v160, 0
	v_mul_lo_u32 v176, s23, v161
	v_mad_u64_u32 v[160:161], s[24:25], s22, v161, 0
	v_add3_u32 v159, v159, v175, v163
	v_add3_u32 v161, v161, v175, v176
	v_lshl_add_u64 v[156:157], v[158:159], 1, v[144:145]
	v_lshl_add_u64 v[158:159], v[160:161], 1, v[144:145]
	v_add3_u32 v155, v155, v175, v164
	v_lshl_add_u64 v[154:155], v[154:155], 1, v[144:145]
	v_ashrrev_i32_e32 v170, 31, v166
	v_ashrrev_i32_e32 v171, 31, v167
	v_ashrrev_i32_e32 v172, 31, v168
	v_ashrrev_i32_e32 v174, 31, v169
	s_andn2_b64 vcc, exec, s[16:17]
	s_mov_b64 s[16:17], -1
	s_waitcnt vmcnt(0)
	v_fmamk_f32 v1, v1, 0x3a800000, v152
	v_fmamk_f32 v153, v153, 0x3a800000, v152
	v_rsq_f32_e32 v160, v1
	v_fmamk_f32 v1, v162, 0x3a800000, v152
	v_rsq_f32_e32 v162, v153
	v_rsq_f32_e32 v164, v1
	v_pk_mul_f32 v[128:129], v[128:129], v[160:161] op_sel_hi:[1,0]
	v_pk_mul_f32 v[126:127], v[126:127], v[160:161] op_sel_hi:[1,0]
	v_pk_mul_f32 v[120:121], v[120:121], v[162:163] op_sel_hi:[1,0]
	v_pk_mul_f32 v[118:119], v[118:119], v[162:163] op_sel_hi:[1,0]
	v_pk_mul_f32 v[112:113], v[112:113], v[162:163] op_sel_hi:[1,0]
	v_pk_mul_f32 v[110:111], v[110:111], v[162:163] op_sel_hi:[1,0]
	v_pk_mul_f32 v[104:105], v[104:105], v[162:163] op_sel_hi:[1,0]
	v_pk_mul_f32 v[102:103], v[102:103], v[162:163] op_sel_hi:[1,0]
	v_pk_mul_f32 v[96:97], v[96:97], v[162:163] op_sel_hi:[1,0]
	v_pk_mul_f32 v[94:95], v[94:95], v[162:163] op_sel_hi:[1,0]
	v_pk_mul_f32 v[162:163], v[84:85], v[164:165] op_sel_hi:[1,0]
	v_cvt_pk_bf16_f32 v84, v126, v127
	v_cvt_pk_bf16_f32 v85, v128, v129
	v_pk_mul_f32 v[124:125], v[124:125], v[160:161] op_sel_hi:[1,0]
	v_pk_mul_f32 v[122:123], v[122:123], v[160:161] op_sel_hi:[1,0]
	v_pk_mul_f32 v[116:117], v[116:117], v[160:161] op_sel_hi:[1,0]
	v_pk_mul_f32 v[114:115], v[114:115], v[160:161] op_sel_hi:[1,0]
	v_pk_mul_f32 v[108:109], v[108:109], v[160:161] op_sel_hi:[1,0]
	v_pk_mul_f32 v[106:107], v[106:107], v[160:161] op_sel_hi:[1,0]
	v_pk_mul_f32 v[160:161], v[86:87], v[164:165] op_sel_hi:[1,0]
	v_cvt_pk_bf16_f32 v86, v122, v123
	v_cvt_pk_bf16_f32 v87, v124, v125
	global_store_dwordx4 v[156:157], v[84:87], off
	v_pk_mul_f32 v[100:101], v[100:101], v[164:165] op_sel_hi:[1,0]
	v_pk_mul_f32 v[98:99], v[98:99], v[164:165] op_sel_hi:[1,0]
	v_cvt_pk_bf16_f32 v84, v114, v115
	v_cvt_pk_bf16_f32 v85, v116, v117
	v_cvt_pk_bf16_f32 v86, v106, v107
	v_cvt_pk_bf16_f32 v87, v108, v109
	global_store_dwordx4 v[156:157], v[84:87], off offset:256
	v_pk_mul_f32 v[92:93], v[92:93], v[164:165] op_sel_hi:[1,0]
	v_pk_mul_f32 v[90:91], v[90:91], v[164:165] op_sel_hi:[1,0]
	v_cvt_pk_bf16_f32 v84, v118, v119
	v_cvt_pk_bf16_f32 v85, v120, v121
	v_cvt_pk_bf16_f32 v86, v110, v111
	v_cvt_pk_bf16_f32 v87, v112, v113
	global_store_dwordx4 v[154:155], v[84:87], off
	v_fmamk_f32 v1, v173, 0x3a800000, v152
	v_pk_mul_f32 v[88:89], v[88:89], v[164:165] op_sel_hi:[1,0]
	v_cvt_pk_bf16_f32 v84, v102, v103
	v_cvt_pk_bf16_f32 v85, v104, v105
	v_cvt_pk_bf16_f32 v86, v94, v95
	v_cvt_pk_bf16_f32 v87, v96, v97
	global_store_dwordx4 v[154:155], v[84:87], off offset:256
	s_nop 1
	v_cvt_pk_bf16_f32 v84, v98, v99
	v_cvt_pk_bf16_f32 v85, v100, v101
	v_cvt_pk_bf16_f32 v86, v90, v91
	v_cvt_pk_bf16_f32 v87, v92, v93
	global_store_dwordx4 v[158:159], v[84:87], off
	s_nop 1
	v_pk_mul_f32 v[84:85], v[82:83], v[164:165] op_sel_hi:[1,0]
	v_cvt_pk_bf16_f32 v82, v160, v161
	v_cvt_pk_bf16_f32 v83, v88, v89
	s_nop 0
	v_cvt_pk_bf16_f32 v84, v84, v85
	v_cvt_pk_bf16_f32 v85, v162, v163
	global_store_dwordx4 v[158:159], v[82:85], off offset:256
	s_nop 1
	v_rsq_f32_e32 v82, v1
	v_mul_lo_u32 v1, s23, v165
	v_mad_u64_u32 v[84:85], s[24:25], s22, v165, 0
	v_add3_u32 v85, v85, v175, v1
	v_lshl_add_u64 v[84:85], v[84:85], 1, v[144:145]
	v_pk_mul_f32 v[80:81], v[80:81], v[82:83] op_sel_hi:[1,0]
	v_pk_mul_f32 v[78:79], v[78:79], v[82:83] op_sel_hi:[1,0]
	v_pk_mul_f32 v[86:87], v[76:77], v[82:83] op_sel_hi:[1,0]
	v_pk_mul_f32 v[76:77], v[74:75], v[82:83] op_sel_hi:[1,0]
	v_cvt_pk_bf16_f32 v74, v78, v79
	v_cvt_pk_bf16_f32 v75, v80, v81
	v_pk_mul_f32 v[70:71], v[70:71], v[82:83] op_sel_hi:[1,0]
	v_cvt_pk_bf16_f32 v76, v76, v77
	v_cvt_pk_bf16_f32 v77, v86, v87
	global_store_dwordx4 v[84:85], v[74:77], off
	v_fmamk_f32 v1, v177, 0x3a800000, v152
	v_pk_mul_f32 v[72:73], v[72:73], v[82:83] op_sel_hi:[1,0]
	v_pk_mul_f32 v[74:75], v[68:69], v[82:83] op_sel_hi:[1,0]
	v_pk_mul_f32 v[68:69], v[66:67], v[82:83] op_sel_hi:[1,0]
	v_cvt_pk_bf16_f32 v66, v70, v71
	v_cvt_pk_bf16_f32 v67, v72, v73
	s_nop 0
	v_cvt_pk_bf16_f32 v68, v68, v69
	v_cvt_pk_bf16_f32 v69, v74, v75
	global_store_dwordx4 v[84:85], v[66:69], off offset:256
	s_nop 1
	v_rsq_f32_e32 v66, v1
	v_mul_lo_u32 v1, s22, v170
	v_mul_lo_u32 v67, s23, v166
	v_mad_u64_u32 v[68:69], s[24:25], s22, v166, 0
	v_add3_u32 v69, v69, v1, v67
	v_lshl_add_u64 v[68:69], v[68:69], 1, v[144:145]
	v_pk_mul_f32 v[64:65], v[64:65], v[66:67] op_sel_hi:[1,0]
	v_pk_mul_f32 v[62:63], v[62:63], v[66:67] op_sel_hi:[1,0]
	v_pk_mul_f32 v[70:71], v[60:61], v[66:67] op_sel_hi:[1,0]
	v_pk_mul_f32 v[60:61], v[58:59], v[66:67] op_sel_hi:[1,0]
	v_cvt_pk_bf16_f32 v58, v62, v63
	v_cvt_pk_bf16_f32 v59, v64, v65
	v_pk_mul_f32 v[54:55], v[54:55], v[66:67] op_sel_hi:[1,0]
	v_cvt_pk_bf16_f32 v60, v60, v61
	v_cvt_pk_bf16_f32 v61, v70, v71
	global_store_dwordx4 v[68:69], v[58:61], off
	v_fmamk_f32 v1, v178, 0x3a800000, v152
	v_pk_mul_f32 v[56:57], v[56:57], v[66:67] op_sel_hi:[1,0]
	v_pk_mul_f32 v[58:59], v[52:53], v[66:67] op_sel_hi:[1,0]
	v_pk_mul_f32 v[52:53], v[50:51], v[66:67] op_sel_hi:[1,0]
	v_cvt_pk_bf16_f32 v50, v54, v55
	v_cvt_pk_bf16_f32 v51, v56, v57
	s_nop 0
	v_cvt_pk_bf16_f32 v52, v52, v53
	v_cvt_pk_bf16_f32 v53, v58, v59
	global_store_dwordx4 v[68:69], v[50:53], off offset:256
	s_nop 1
	v_rsq_f32_e32 v50, v1
	v_mul_lo_u32 v1, s22, v171
	v_mul_lo_u32 v51, s23, v167
	v_mad_u64_u32 v[52:53], s[24:25], s22, v167, 0
	v_add3_u32 v53, v53, v1, v51
	v_lshl_add_u64 v[52:53], v[52:53], 1, v[144:145]
	v_pk_mul_f32 v[48:49], v[48:49], v[50:51] op_sel_hi:[1,0]
	v_pk_mul_f32 v[46:47], v[46:47], v[50:51] op_sel_hi:[1,0]
	v_pk_mul_f32 v[54:55], v[44:45], v[50:51] op_sel_hi:[1,0]
	v_pk_mul_f32 v[44:45], v[42:43], v[50:51] op_sel_hi:[1,0]
	v_cvt_pk_bf16_f32 v42, v46, v47
	v_cvt_pk_bf16_f32 v43, v48, v49
	v_pk_mul_f32 v[38:39], v[38:39], v[50:51] op_sel_hi:[1,0]
	v_cvt_pk_bf16_f32 v44, v44, v45
	v_cvt_pk_bf16_f32 v45, v54, v55
	global_store_dwordx4 v[52:53], v[42:45], off
	v_fmamk_f32 v1, v179, 0x3a800000, v152
	v_pk_mul_f32 v[40:41], v[40:41], v[50:51] op_sel_hi:[1,0]
	v_pk_mul_f32 v[42:43], v[36:37], v[50:51] op_sel_hi:[1,0]
	v_pk_mul_f32 v[36:37], v[34:35], v[50:51] op_sel_hi:[1,0]
	v_cvt_pk_bf16_f32 v34, v38, v39
	v_cvt_pk_bf16_f32 v35, v40, v41
	s_nop 0
	v_cvt_pk_bf16_f32 v36, v36, v37
	v_cvt_pk_bf16_f32 v37, v42, v43
	global_store_dwordx4 v[52:53], v[34:37], off offset:256
	s_nop 1
	v_rsq_f32_e32 v34, v1
	v_mul_lo_u32 v1, s22, v172
	v_mul_lo_u32 v35, s23, v168
	v_mad_u64_u32 v[36:37], s[24:25], s22, v168, 0
	v_add3_u32 v37, v37, v1, v35
	v_lshl_add_u64 v[36:37], v[36:37], 1, v[144:145]
	v_pk_mul_f32 v[32:33], v[32:33], v[34:35] op_sel_hi:[1,0]
	v_pk_mul_f32 v[30:31], v[30:31], v[34:35] op_sel_hi:[1,0]
	v_pk_mul_f32 v[38:39], v[28:29], v[34:35] op_sel_hi:[1,0]
	v_pk_mul_f32 v[28:29], v[26:27], v[34:35] op_sel_hi:[1,0]
	v_cvt_pk_bf16_f32 v26, v30, v31
	v_cvt_pk_bf16_f32 v27, v32, v33
	v_pk_mul_f32 v[22:23], v[22:23], v[34:35] op_sel_hi:[1,0]
	v_cvt_pk_bf16_f32 v28, v28, v29
	v_cvt_pk_bf16_f32 v29, v38, v39
	global_store_dwordx4 v[36:37], v[26:29], off
	v_fmamk_f32 v1, v180, 0x3a800000, v152
	v_pk_mul_f32 v[24:25], v[24:25], v[34:35] op_sel_hi:[1,0]
	v_pk_mul_f32 v[26:27], v[20:21], v[34:35] op_sel_hi:[1,0]
	v_pk_mul_f32 v[20:21], v[18:19], v[34:35] op_sel_hi:[1,0]
	v_cvt_pk_bf16_f32 v18, v22, v23
	v_cvt_pk_bf16_f32 v19, v24, v25
	s_nop 0
	v_cvt_pk_bf16_f32 v20, v20, v21
	v_cvt_pk_bf16_f32 v21, v26, v27
	global_store_dwordx4 v[36:37], v[18:21], off offset:256
	s_nop 1
	v_rsq_f32_e32 v18, v1
	v_mul_lo_u32 v1, s22, v174
	v_mul_lo_u32 v19, s23, v169
	v_mad_u64_u32 v[20:21], s[22:23], s22, v169, 0
	v_add3_u32 v21, v21, v1, v19
	v_lshl_add_u64 v[20:21], v[20:21], 1, v[144:145]
	v_pk_mul_f32 v[16:17], v[16:17], v[18:19] op_sel_hi:[1,0]
	v_pk_mul_f32 v[14:15], v[14:15], v[18:19] op_sel_hi:[1,0]
	v_pk_mul_f32 v[22:23], v[12:13], v[18:19] op_sel_hi:[1,0]
	v_pk_mul_f32 v[12:13], v[10:11], v[18:19] op_sel_hi:[1,0]
	v_cvt_pk_bf16_f32 v10, v14, v15
	v_cvt_pk_bf16_f32 v11, v16, v17
	v_pk_mul_f32 v[8:9], v[8:9], v[18:19] op_sel_hi:[1,0]
	v_cvt_pk_bf16_f32 v12, v12, v13
	v_cvt_pk_bf16_f32 v13, v22, v23
	global_store_dwordx4 v[20:21], v[10:13], off
	v_pk_mul_f32 v[6:7], v[6:7], v[18:19] op_sel_hi:[1,0]
	s_nop 0
	v_pk_mul_f32 v[10:11], v[4:5], v[18:19] op_sel_hi:[1,0]
	v_pk_mul_f32 v[4:5], v[2:3], v[18:19] op_sel_hi:[1,0]
	v_cvt_pk_bf16_f32 v2, v6, v7
	v_cvt_pk_bf16_f32 v3, v8, v9
	s_nop 0
	v_cvt_pk_bf16_f32 v4, v4, v5
	v_cvt_pk_bf16_f32 v5, v10, v11
	global_store_dwordx4 v[20:21], v[2:5], off offset:256
.Lepi_in_join:
	s_cbranch_vccnz .LBB0_259
	s_nop 0
	v_mov_b32_e32 v2, v0
	v_mov_b32_e32 v3, v0
	v_mov_b32_e32 v1, v0
	v_mov_b64_e32 v[4:5], v[2:3]
	v_mov_b64_e32 v[2:3], v[0:1]
	s_andn2_b64 vcc, exec, s[4:5]
	s_nop 0
	v_mfma_f32_16x16x32_bf16 v[2:5], v[2:5], v[2:5], 0
	s_cbranch_vccnz .LBB0_258
	s_barrier
	s_branch .LBB0_258
.Lepi_in_nt:
	v_lshl_add_u32 v154, s20, 8, v146
	v_ashrrev_i32_e32 v155, 31, v154
	v_lshl_add_u64 v[156:157], v[154:155], 2, s[84:85]
	global_load_dword v1, v[156:157], off
	global_load_dword v153, v[156:157], off offset:64
	global_load_dword v162, v[156:157], off offset:128
	global_load_dword v173, v[156:157], off offset:192
	global_load_dword v177, v[156:157], off offset:512
	global_load_dword v178, v[156:157], off offset:576
	global_load_dword v179, v[156:157], off offset:640
	global_load_dword v180, v[156:157], off offset:704
	v_add_u32_e32 v144, s11, v148
	v_or_b32_e32 v160, 16, v154
	v_or_b32_e32 v161, 32, v154
	v_ashrrev_i32_e32 v145, 31, v144
	v_or_b32_e32 v165, 48, v154
	v_add_u32_e32 v166, 0x80, v154
	v_add_u32_e32 v167, 0x90, v154
	v_add_u32_e32 v168, 0xa0, v154
	v_add_u32_e32 v169, 0xb0, v154
	v_mul_lo_u32 v163, s23, v154
	v_mad_u64_u32 v[158:159], s[26:27], s22, v154, 0
	v_lshl_add_u64 v[144:145], v[144:145], 1, s[24:25]
	v_mul_lo_u32 v175, s22, v155
	v_mul_lo_u32 v164, s23, v160
	v_mad_u64_u32 v[154:155], s[24:25], s22, v160, 0
	v_mul_lo_u32 v176, s23, v161
	v_mad_u64_u32 v[160:161], s[24:25], s22, v161, 0
	v_add3_u32 v159, v159, v175, v163
	v_add3_u32 v161, v161, v175, v176
	v_lshl_add_u64 v[156:157], v[158:159], 1, v[144:145]
	v_lshl_add_u64 v[158:159], v[160:161], 1, v[144:145]
	v_add3_u32 v155, v155, v175, v164
	v_lshl_add_u64 v[154:155], v[154:155], 1, v[144:145]
	v_ashrrev_i32_e32 v170, 31, v166
	v_ashrrev_i32_e32 v171, 31, v167
	v_ashrrev_i32_e32 v172, 31, v168
	v_ashrrev_i32_e32 v174, 31, v169
	s_andn2_b64 vcc, exec, s[16:17]
	s_mov_b64 s[16:17], -1
	s_waitcnt vmcnt(0)
	v_fmamk_f32 v1, v1, 0x3a800000, v152
	v_fmamk_f32 v153, v153, 0x3a800000, v152
	v_rsq_f32_e32 v160, v1
	v_fmamk_f32 v1, v162, 0x3a800000, v152
	v_rsq_f32_e32 v162, v153
	v_rsq_f32_e32 v164, v1
	v_pk_mul_f32 v[128:129], v[128:129], v[160:161] op_sel_hi:[1,0]
	v_pk_mul_f32 v[126:127], v[126:127], v[160:161] op_sel_hi:[1,0]
	v_pk_mul_f32 v[120:121], v[120:121], v[162:163] op_sel_hi:[1,0]
	v_pk_mul_f32 v[118:119], v[118:119], v[162:163] op_sel_hi:[1,0]
	v_pk_mul_f32 v[112:113], v[112:113], v[162:163] op_sel_hi:[1,0]
	v_pk_mul_f32 v[110:111], v[110:111], v[162:163] op_sel_hi:[1,0]
	v_pk_mul_f32 v[104:105], v[104:105], v[162:163] op_sel_hi:[1,0]
	v_pk_mul_f32 v[102:103], v[102:103], v[162:163] op_sel_hi:[1,0]
	v_pk_mul_f32 v[96:97], v[96:97], v[162:163] op_sel_hi:[1,0]
	v_pk_mul_f32 v[94:95], v[94:95], v[162:163] op_sel_hi:[1,0]
	v_pk_mul_f32 v[162:163], v[84:85], v[164:165] op_sel_hi:[1,0]
	v_cvt_pk_bf16_f32 v84, v126, v127
	v_cvt_pk_bf16_f32 v85, v128, v129
	v_pk_mul_f32 v[124:125], v[124:125], v[160:161] op_sel_hi:[1,0]
	v_pk_mul_f32 v[122:123], v[122:123], v[160:161] op_sel_hi:[1,0]
	v_pk_mul_f32 v[116:117], v[116:117], v[160:161] op_sel_hi:[1,0]
	v_pk_mul_f32 v[114:115], v[114:115], v[160:161] op_sel_hi:[1,0]
	v_pk_mul_f32 v[108:109], v[108:109], v[160:161] op_sel_hi:[1,0]
	v_pk_mul_f32 v[106:107], v[106:107], v[160:161] op_sel_hi:[1,0]
	v_pk_mul_f32 v[160:161], v[86:87], v[164:165] op_sel_hi:[1,0]
	v_cvt_pk_bf16_f32 v86, v122, v123
	v_cvt_pk_bf16_f32 v87, v124, v125
	global_store_dwordx4 v[156:157], v[84:87], off nt
	v_pk_mul_f32 v[100:101], v[100:101], v[164:165] op_sel_hi:[1,0]
	v_pk_mul_f32 v[98:99], v[98:99], v[164:165] op_sel_hi:[1,0]
	v_cvt_pk_bf16_f32 v84, v114, v115
	v_cvt_pk_bf16_f32 v85, v116, v117
	v_cvt_pk_bf16_f32 v86, v106, v107
	v_cvt_pk_bf16_f32 v87, v108, v109
	global_store_dwordx4 v[156:157], v[84:87], off offset:256 nt
	v_pk_mul_f32 v[92:93], v[92:93], v[164:165] op_sel_hi:[1,0]
	v_pk_mul_f32 v[90:91], v[90:91], v[164:165] op_sel_hi:[1,0]
	v_cvt_pk_bf16_f32 v84, v118, v119
	v_cvt_pk_bf16_f32 v85, v120, v121
	v_cvt_pk_bf16_f32 v86, v110, v111
	v_cvt_pk_bf16_f32 v87, v112, v113
	global_store_dwordx4 v[154:155], v[84:87], off nt
	v_fmamk_f32 v1, v173, 0x3a800000, v152
	v_pk_mul_f32 v[88:89], v[88:89], v[164:165] op_sel_hi:[1,0]
	v_cvt_pk_bf16_f32 v84, v102, v103
	v_cvt_pk_bf16_f32 v85, v104, v105
	v_cvt_pk_bf16_f32 v86, v94, v95
	v_cvt_pk_bf16_f32 v87, v96, v97
	global_store_dwordx4 v[154:155], v[84:87], off offset:256 nt
	s_nop 1
	v_cvt_pk_bf16_f32 v84, v98, v99
	v_cvt_pk_bf16_f32 v85, v100, v101
	v_cvt_pk_bf16_f32 v86, v90, v91
	v_cvt_pk_bf16_f32 v87, v92, v93
	global_store_dwordx4 v[158:159], v[84:87], off nt
	s_nop 1
	v_pk_mul_f32 v[84:85], v[82:83], v[164:165] op_sel_hi:[1,0]
	v_cvt_pk_bf16_f32 v82, v160, v161
	v_cvt_pk_bf16_f32 v83, v88, v89
	s_nop 0
	v_cvt_pk_bf16_f32 v84, v84, v85
	v_cvt_pk_bf16_f32 v85, v162, v163
	global_store_dwordx4 v[158:159], v[82:85], off offset:256 nt
	s_nop 1
	v_rsq_f32_e32 v82, v1
	v_mul_lo_u32 v1, s23, v165
	v_mad_u64_u32 v[84:85], s[24:25], s22, v165, 0
	v_add3_u32 v85, v85, v175, v1
	v_lshl_add_u64 v[84:85], v[84:85], 1, v[144:145]
	v_pk_mul_f32 v[80:81], v[80:81], v[82:83] op_sel_hi:[1,0]
	v_pk_mul_f32 v[78:79], v[78:79], v[82:83] op_sel_hi:[1,0]
	v_pk_mul_f32 v[86:87], v[76:77], v[82:83] op_sel_hi:[1,0]
	v_pk_mul_f32 v[76:77], v[74:75], v[82:83] op_sel_hi:[1,0]
	v_cvt_pk_bf16_f32 v74, v78, v79
	v_cvt_pk_bf16_f32 v75, v80, v81
	v_pk_mul_f32 v[70:71], v[70:71], v[82:83] op_sel_hi:[1,0]
	v_cvt_pk_bf16_f32 v76, v76, v77
	v_cvt_pk_bf16_f32 v77, v86, v87
	global_store_dwordx4 v[84:85], v[74:77], off nt
	v_fmamk_f32 v1, v177, 0x3a800000, v152
	v_pk_mul_f32 v[72:73], v[72:73], v[82:83] op_sel_hi:[1,0]
	v_pk_mul_f32 v[74:75], v[68:69], v[82:83] op_sel_hi:[1,0]
	v_pk_mul_f32 v[68:69], v[66:67], v[82:83] op_sel_hi:[1,0]
	v_cvt_pk_bf16_f32 v66, v70, v71
	v_cvt_pk_bf16_f32 v67, v72, v73
	s_nop 0
	v_cvt_pk_bf16_f32 v68, v68, v69
	v_cvt_pk_bf16_f32 v69, v74, v75
	global_store_dwordx4 v[84:85], v[66:69], off offset:256 nt
	s_nop 1
	v_rsq_f32_e32 v66, v1
	v_mul_lo_u32 v1, s22, v170
	v_mul_lo_u32 v67, s23, v166
	v_mad_u64_u32 v[68:69], s[24:25], s22, v166, 0
	v_add3_u32 v69, v69, v1, v67
	v_lshl_add_u64 v[68:69], v[68:69], 1, v[144:145]
	v_pk_mul_f32 v[64:65], v[64:65], v[66:67] op_sel_hi:[1,0]
	v_pk_mul_f32 v[62:63], v[62:63], v[66:67] op_sel_hi:[1,0]
	v_pk_mul_f32 v[70:71], v[60:61], v[66:67] op_sel_hi:[1,0]
	v_pk_mul_f32 v[60:61], v[58:59], v[66:67] op_sel_hi:[1,0]
	v_cvt_pk_bf16_f32 v58, v62, v63
	v_cvt_pk_bf16_f32 v59, v64, v65
	v_pk_mul_f32 v[54:55], v[54:55], v[66:67] op_sel_hi:[1,0]
	v_cvt_pk_bf16_f32 v60, v60, v61
	v_cvt_pk_bf16_f32 v61, v70, v71
	global_store_dwordx4 v[68:69], v[58:61], off nt
	v_fmamk_f32 v1, v178, 0x3a800000, v152
	v_pk_mul_f32 v[56:57], v[56:57], v[66:67] op_sel_hi:[1,0]
	v_pk_mul_f32 v[58:59], v[52:53], v[66:67] op_sel_hi:[1,0]
	v_pk_mul_f32 v[52:53], v[50:51], v[66:67] op_sel_hi:[1,0]
	v_cvt_pk_bf16_f32 v50, v54, v55
	v_cvt_pk_bf16_f32 v51, v56, v57
	s_nop 0
	v_cvt_pk_bf16_f32 v52, v52, v53
	v_cvt_pk_bf16_f32 v53, v58, v59
	global_store_dwordx4 v[68:69], v[50:53], off offset:256 nt
	s_nop 1
	v_rsq_f32_e32 v50, v1
	v_mul_lo_u32 v1, s22, v171
	v_mul_lo_u32 v51, s23, v167
	v_mad_u64_u32 v[52:53], s[24:25], s22, v167, 0
	v_add3_u32 v53, v53, v1, v51
	v_lshl_add_u64 v[52:53], v[52:53], 1, v[144:145]
	v_pk_mul_f32 v[48:49], v[48:49], v[50:51] op_sel_hi:[1,0]
	v_pk_mul_f32 v[46:47], v[46:47], v[50:51] op_sel_hi:[1,0]
	v_pk_mul_f32 v[54:55], v[44:45], v[50:51] op_sel_hi:[1,0]
	v_pk_mul_f32 v[44:45], v[42:43], v[50:51] op_sel_hi:[1,0]
	v_cvt_pk_bf16_f32 v42, v46, v47
	v_cvt_pk_bf16_f32 v43, v48, v49
	v_pk_mul_f32 v[38:39], v[38:39], v[50:51] op_sel_hi:[1,0]
	v_cvt_pk_bf16_f32 v44, v44, v45
	v_cvt_pk_bf16_f32 v45, v54, v55
	global_store_dwordx4 v[52:53], v[42:45], off nt
	v_fmamk_f32 v1, v179, 0x3a800000, v152
	v_pk_mul_f32 v[40:41], v[40:41], v[50:51] op_sel_hi:[1,0]
	v_pk_mul_f32 v[42:43], v[36:37], v[50:51] op_sel_hi:[1,0]
	v_pk_mul_f32 v[36:37], v[34:35], v[50:51] op_sel_hi:[1,0]
	v_cvt_pk_bf16_f32 v34, v38, v39
	v_cvt_pk_bf16_f32 v35, v40, v41
	s_nop 0
	v_cvt_pk_bf16_f32 v36, v36, v37
	v_cvt_pk_bf16_f32 v37, v42, v43
	global_store_dwordx4 v[52:53], v[34:37], off offset:256 nt
	s_nop 1
	v_rsq_f32_e32 v34, v1
	v_mul_lo_u32 v1, s22, v172
	v_mul_lo_u32 v35, s23, v168
	v_mad_u64_u32 v[36:37], s[24:25], s22, v168, 0
	v_add3_u32 v37, v37, v1, v35
	v_lshl_add_u64 v[36:37], v[36:37], 1, v[144:145]
	v_pk_mul_f32 v[32:33], v[32:33], v[34:35] op_sel_hi:[1,0]
	v_pk_mul_f32 v[30:31], v[30:31], v[34:35] op_sel_hi:[1,0]
	v_pk_mul_f32 v[38:39], v[28:29], v[34:35] op_sel_hi:[1,0]
	v_pk_mul_f32 v[28:29], v[26:27], v[34:35] op_sel_hi:[1,0]
	v_cvt_pk_bf16_f32 v26, v30, v31
	v_cvt_pk_bf16_f32 v27, v32, v33
	v_pk_mul_f32 v[22:23], v[22:23], v[34:35] op_sel_hi:[1,0]
	v_cvt_pk_bf16_f32 v28, v28, v29
	v_cvt_pk_bf16_f32 v29, v38, v39
	global_store_dwordx4 v[36:37], v[26:29], off nt
	v_fmamk_f32 v1, v180, 0x3a800000, v152
	v_pk_mul_f32 v[24:25], v[24:25], v[34:35] op_sel_hi:[1,0]
	v_pk_mul_f32 v[26:27], v[20:21], v[34:35] op_sel_hi:[1,0]
	v_pk_mul_f32 v[20:21], v[18:19], v[34:35] op_sel_hi:[1,0]
	v_cvt_pk_bf16_f32 v18, v22, v23
	v_cvt_pk_bf16_f32 v19, v24, v25
	s_nop 0
	v_cvt_pk_bf16_f32 v20, v20, v21
	v_cvt_pk_bf16_f32 v21, v26, v27
	global_store_dwordx4 v[36:37], v[18:21], off offset:256 nt
	s_nop 1
	v_rsq_f32_e32 v18, v1
	v_mul_lo_u32 v1, s22, v174
	v_mul_lo_u32 v19, s23, v169
	v_mad_u64_u32 v[20:21], s[22:23], s22, v169, 0
	v_add3_u32 v21, v21, v1, v19
	v_lshl_add_u64 v[20:21], v[20:21], 1, v[144:145]
	v_pk_mul_f32 v[16:17], v[16:17], v[18:19] op_sel_hi:[1,0]
	v_pk_mul_f32 v[14:15], v[14:15], v[18:19] op_sel_hi:[1,0]
	v_pk_mul_f32 v[22:23], v[12:13], v[18:19] op_sel_hi:[1,0]
	v_pk_mul_f32 v[12:13], v[10:11], v[18:19] op_sel_hi:[1,0]
	v_cvt_pk_bf16_f32 v10, v14, v15
	v_cvt_pk_bf16_f32 v11, v16, v17
	v_pk_mul_f32 v[8:9], v[8:9], v[18:19] op_sel_hi:[1,0]
	v_cvt_pk_bf16_f32 v12, v12, v13
	v_cvt_pk_bf16_f32 v13, v22, v23
	global_store_dwordx4 v[20:21], v[10:13], off nt
	v_pk_mul_f32 v[6:7], v[6:7], v[18:19] op_sel_hi:[1,0]
	s_nop 0
	v_pk_mul_f32 v[10:11], v[4:5], v[18:19] op_sel_hi:[1,0]
	v_pk_mul_f32 v[4:5], v[2:3], v[18:19] op_sel_hi:[1,0]
	v_cvt_pk_bf16_f32 v2, v6, v7
	v_cvt_pk_bf16_f32 v3, v8, v9
	s_nop 0
	v_cvt_pk_bf16_f32 v4, v4, v5
	v_cvt_pk_bf16_f32 v5, v10, v11
	global_store_dwordx4 v[20:21], v[2:5], off offset:256 nt
	s_branch .Lepi_in_join
